# v026 + attn_post: the three group-output loads issued together with the three LSE loads (one memory round trip per token instead of two), top-of-loop store drain removed
# baseline (speedup 1.0000x reference)
; __device__ __forceinline__ unsigned pk2(float lo, float hi) { return cvt_pk_bf16(lo, hi); }
; __device__ __forceinline__ float fexp(float x) { return __builtin_amdgcn_exp2f(x * 1.44269504089f); }
; __device__ __forceinline__ void phase_attn_post(const Frame& F, const Args& a) {
;     ...
;     for (int t = F.gw; t < T; t += F.NGW) {
;         const float l0 = LSE[((size_t)0 * T + t) * 4 + h], l1 = LSE[((size_t)1 * T + t) * 4 + h], l2 = LSE[((size_t)2 * T + t) * 4 + h];
;         const float m = fmaxf(l0, fmaxf(l1, l2)); float w0 = fexp(l0 - m), w1 = fexp(l1 - m), w2 = fexp(l2 - m); const float inv = 1.0f / (w0 + w1 + w2); w0 *= inv; w1 *= inv; w2 *= inv;
;         const v4u o0 = *(const v4u*)(OA + ((size_t)0 * T + t) * 512 + c0), o1 = *(const v4u*)(OA + ((size_t)1 * T + t) * 512 + c0), o2 = *(const v4u*)(OA + ((size_t)2 * T + t) * 512 + c0);
;         v4u w;
; #pragma unroll
;         for (int q = 0; q < 4; ++q) w[q] = pk2(w0 * bf_lo(o0[q]) + w1 * bf_lo(o1[q]) + w2 * bf_lo(o2[q]), w0 * bf_hi(o0[q]) + w1 * bf_hi(o1[q]) + w2 * bf_hi(o2[q]));
;         *(v4u*)(YA + (size_t)t * 512 + c0) = w;
.LBB0_1061:
	s_nop 0
	v_lshl_add_u64 v[6:7], s[12:13], 0, v[2:3]
	v_add_co_u32_e32 v8, vcc, 0x41e00000, v6
	s_nop 0
	v_lshl_add_u64 v[18:19], s[12:13], 0, v[0:1]
	v_addc_co_u32_e32 v9, vcc, 0, v7, vcc
	global_load_dword v4, v[8:9], off
	v_add_co_u32_e32 v8, vcc, 0x41ea0000, v6
	s_mov_b32 s7, 0x19e00000
	s_nop 0
	v_addc_co_u32_e32 v9, vcc, 0, v7, vcc
	v_add_co_u32_e32 v6, vcc, 0x41f40000, v6
	global_load_dword v8, v[8:9], off
	s_nop 0
	v_addc_co_u32_e32 v7, vcc, 0, v7, vcc
	global_load_dword v9, v[6:7], off
	s_mov_b64 s[24:25], 0x19e00000
	v_lshl_add_u64 v[84:85], v[18:19], 0, s[24:25]
	global_load_dwordx4 v[72:75], v[84:85], off
	s_mov_b64 s[24:25], 0x1c600000
	v_lshl_add_u64 v[84:85], v[18:19], 0, s[24:25]
	global_load_dwordx4 v[76:79], v[84:85], off
	s_mov_b64 s[24:25], 0x1ee00000
	v_lshl_add_u64 v[84:85], v[18:19], 0, s[24:25]
	global_load_dwordx4 v[80:83], v[84:85], off
	s_add_i32 s6, s6, s8
	v_lshl_add_u64 v[0:1], v[0:1], 0, s[10:11]
	v_lshl_add_u64 v[2:3], v[2:3], 0, s[14:15]
	s_cmp_lt_i32 s6, 0xa000
	s_waitcnt vmcnt(3)
	v_max3_f32 v10, v4, v8, v9
	v_sub_f32_e32 v4, v4, v10
	v_mul_f32_e32 v4, 0x3fb8aa3b, v4
	v_exp_f32_e32 v7, v4
	v_sub_f32_e32 v4, v8, v10
	v_mul_f32_e32 v4, 0x3fb8aa3b, v4
	v_exp_f32_e32 v6, v4
	v_sub_f32_e32 v4, v9, v10
	v_mul_f32_e32 v4, 0x3fb8aa3b, v4
	v_exp_f32_e32 v4, v4
	v_add_f32_e32 v8, v7, v6
	v_add_f32_e32 v8, v4, v8
	v_div_scale_f32 v9, s[16:17], v8, v8, 1.0
	v_rcp_f32_e32 v10, v9
	s_nop 0
	v_fma_f32 v11, -v9, v10, 1.0
	v_fmac_f32_e32 v10, v11, v10
	v_div_scale_f32 v11, vcc, 1.0, v8, 1.0
	v_mul_f32_e32 v12, v11, v10
	v_fma_f32 v13, -v9, v12, v11
	v_fmac_f32_e32 v12, v13, v10
	v_fma_f32 v9, -v9, v12, v11
	v_div_fmas_f32 v9, v9, v10, v12
	v_add_co_u32_e32 v22, vcc, s7, v18
	s_mov_b32 s7, 0x1c600000
	s_nop 0
	v_addc_co_u32_e32 v23, vcc, 0, v19, vcc
	v_add_co_u32_e32 v14, vcc, s7, v18
	s_nop 0
	s_nop 0
	v_addc_co_u32_e32 v15, vcc, 0, v19, vcc
	s_nop 0
	s_mov_b32 s7, 0x1ee00000
	v_add_co_u32_e32 v18, vcc, s7, v18
	v_div_fixup_f32 v8, v9, v8, 1.0
	s_nop 0
	v_addc_co_u32_e32 v19, vcc, 0, v19, vcc
	s_nop 0
	v_mul_f32_e32 v4, v4, v8
	v_pk_mul_f32 v[24:25], v[6:7], v[8:9] op_sel_hi:[1,0]
	s_waitcnt vmcnt(2)
	v_mov_b32_e32 v10, v72
	v_mov_b32_e32 v11, v73
	v_mov_b32_e32 v12, v74
	v_mov_b32_e32 v13, v75
	v_lshlrev_b32_e32 v8, 16, v10
	v_and_b32_e32 v7, 0xffff0000, v10
	v_lshlrev_b32_e32 v10, 16, v11
	s_waitcnt vmcnt(1)
	v_mov_b32_e32 v14, v76
	v_mov_b32_e32 v15, v77
	v_mov_b32_e32 v16, v78
	v_mov_b32_e32 v17, v79
	v_and_b32_e32 v9, 0xffff0000, v14
	v_lshlrev_b32_e32 v6, 16, v14
	v_pk_mul_f32 v[8:9], v[24:25], v[8:9] op_sel:[1,0] op_sel_hi:[0,1]
	v_pk_fma_f32 v[6:7], v[24:25], v[6:7], v[8:9]
	v_and_b32_e32 v9, 0xffff0000, v11
	v_and_b32_e32 v11, 0xffff0000, v15
	v_lshlrev_b32_e32 v8, 16, v15
	v_pk_mul_f32 v[10:11], v[24:25], v[10:11] op_sel:[1,0] op_sel_hi:[0,1]
	s_waitcnt vmcnt(0)
	v_mov_b32_e32 v18, v80
	v_mov_b32_e32 v19, v81
	v_mov_b32_e32 v20, v82
	v_mov_b32_e32 v21, v83
	v_lshlrev_b32_e32 v26, 16, v18
	v_and_b32_e32 v27, 0xffff0000, v18
	v_lshlrev_b32_e32 v14, 16, v19
	v_and_b32_e32 v15, 0xffff0000, v19
	v_pk_fma_f32 v[8:9], v[24:25], v[8:9], v[10:11]
	v_pk_fma_f32 v[6:7], v[4:5], v[26:27], v[6:7] op_sel_hi:[0,1,1]
	v_pk_fma_f32 v[8:9], v[4:5], v[14:15], v[8:9] op_sel_hi:[0,1,1]
	v_lshlrev_b32_e32 v10, 16, v12
	v_and_b32_e32 v11, 0xffff0000, v16
	v_cvt_pk_bf16_f32 v6, v6, v7
	v_cvt_pk_bf16_f32 v7, v8, v9
	v_lshlrev_b32_e32 v8, 16, v16
	v_and_b32_e32 v9, 0xffff0000, v12
	v_pk_mul_f32 v[10:11], v[24:25], v[10:11] op_sel:[1,0] op_sel_hi:[0,1]
	v_pk_fma_f32 v[8:9], v[24:25], v[8:9], v[10:11]
	v_and_b32_e32 v11, 0xffff0000, v13
	v_lshlrev_b32_e32 v12, 16, v13
	v_and_b32_e32 v13, 0xffff0000, v17
	v_lshlrev_b32_e32 v10, 16, v17
	v_pk_mul_f32 v[12:13], v[24:25], v[12:13] op_sel:[1,0] op_sel_hi:[0,1]
	v_lshlrev_b32_e32 v14, 16, v20
	v_and_b32_e32 v15, 0xffff0000, v20
	v_pk_fma_f32 v[10:11], v[24:25], v[10:11], v[12:13]
	v_lshlrev_b32_e32 v12, 16, v21
	v_and_b32_e32 v13, 0xffff0000, v21
	v_pk_fma_f32 v[8:9], v[4:5], v[14:15], v[8:9] op_sel_hi:[0,1,1]
	v_pk_fma_f32 v[10:11], v[4:5], v[12:13], v[10:11] op_sel_hi:[0,1,1]
	v_cvt_pk_bf16_f32 v8, v8, v9
	v_cvt_pk_bf16_f32 v9, v10, v11
	global_store_dwordx4 v[22:23], v[6:9], off
	s_cbranch_scc1 .LBB0_1061
